# sparse work split: cost model counts a list's partly filled last tile by its active waves (v75 otherwise)
# baseline (speedup 1.0000x reference)
.LBB0_789:
	s_or_b64 exec, exec, s[4:5]
	v_and_b32_e32 v1, 63, v0
	s_cmp_lt_u32 s33, 64
	v_and_b32_e32 v7, 64, v6
	v_cmp_gt_u32_e32 vcc, 32, v1
	s_waitcnt lgkmcnt(0)
	s_barrier
	s_cbranch_scc0 .LBB0_793
	v_lshlrev_b32_e32 v20, 6, v1
	v_add_u32_e32 v2, 0, v20
	v_add_u32_e32 v16, 0x20400, v2
	ds_read_b128 v[2:5], v16
	s_movk_i32 s6, 0xff
	ds_read_b128 v[8:11], v16 offset:16
	ds_read_b128 v[12:15], v16 offset:32
	ds_read_b128 v[16:19], v16 offset:48
	v_add_u32_e32 v38, -2, v6
	s_add_i32 s16, 0, 0x21400
	s_waitcnt lgkmcnt(3)
	v_add_u32_e32 v2, 0xff, v2
	v_add_u32_e32 v3, 0xff, v3
	v_bfe_u32 v60, v2, 5, 3
	v_lshrrev_b32_e32 v24, 8, v2
	v_add_u32_e32 v60, -3, v60
	v_max_i32_e32 v60, 0, v60
	v_lshl_add_u32 v24, v24, 3, v60
	v_bfe_u32 v60, v3, 5, 3
	v_lshrrev_b32_e32 v23, 8, v3
	v_add_u32_e32 v60, -3, v60
	v_max_i32_e32 v60, 0, v60
	v_lshl_add_u32 v23, v23, 3, v60
	v_cmp_lt_u32_e64 s[4:5], s6, v2
	v_lshrrev_b32_e32 v21, 8, v2
	v_cndmask_b32_e64 v24, 0, v24, s[4:5]
	v_cmp_lt_u32_e64 s[4:5], s6, v3
	v_lshrrev_b32_e32 v22, 8, v3
	s_waitcnt lgkmcnt(2)
	v_add_u32_e32 v8, 0xff, v8
	v_cndmask_b32_e64 v2, 0, v23, s[4:5]
	v_add_u32_e32 v23, v2, v24
	v_add_u32_e32 v2, 0xff, v4
	v_bfe_u32 v60, v2, 5, 3
	v_lshrrev_b32_e32 v4, 8, v2
	v_add_u32_e32 v60, -3, v60
	v_max_i32_e32 v60, 0, v60
	v_lshl_add_u32 v4, v4, 3, v60
	v_cmp_lt_u32_e64 s[4:5], s6, v2
	v_lshrrev_b32_e32 v3, 8, v2
	v_bfe_u32 v60, v8, 5, 3
	v_lshrrev_b32_e32 v26, 8, v8
	v_add_u32_e32 v60, -3, v60
	v_max_i32_e32 v60, 0, v60
	v_lshl_add_u32 v26, v26, 3, v60
	v_cndmask_b32_e64 v2, 0, v4, s[4:5]
	v_add_u32_e32 v4, 0xff, v5
	v_bfe_u32 v60, v4, 5, 3
	v_lshrrev_b32_e32 v25, 8, v4
	v_add_u32_e32 v60, -3, v60
	v_max_i32_e32 v60, 0, v60
	v_lshl_add_u32 v25, v25, 3, v60
	v_cmp_lt_u32_e64 s[4:5], s6, v4
	v_add_u32_e32 v9, 0xff, v9
	v_lshrrev_b32_e32 v5, 8, v4
	v_cndmask_b32_e64 v4, 0, v25, s[4:5]
	v_cmp_lt_u32_e64 s[4:5], s6, v8
	v_bfe_u32 v60, v9, 5, 3
	v_lshrrev_b32_e32 v27, 8, v9
	v_add_u32_e32 v60, -3, v60
	v_max_i32_e32 v60, 0, v60
	v_lshl_add_u32 v27, v27, 3, v60
	v_add_u32_e32 v10, 0xff, v10
	v_add_u32_e32 v22, v22, v21
	v_lshrrev_b32_e32 v25, 8, v8
	v_cndmask_b32_e64 v8, 0, v26, s[4:5]
	v_cmp_lt_u32_e64 s[4:5], s6, v9
	v_bfe_u32 v60, v10, 5, 3
	v_lshrrev_b32_e32 v28, 8, v10
	v_add_u32_e32 v60, -3, v60
	v_max_i32_e32 v60, 0, v60
	v_lshl_add_u32 v28, v28, 3, v60
	v_add_u32_e32 v11, 0xff, v11
	v_lshrrev_b32_e32 v26, 8, v9
	v_cndmask_b32_e64 v9, 0, v27, s[4:5]
	v_cmp_lt_u32_e64 s[4:5], s6, v10
	v_bfe_u32 v60, v11, 5, 3
	v_lshrrev_b32_e32 v29, 8, v11
	v_add_u32_e32 v60, -3, v60
	v_max_i32_e32 v60, 0, v60
	v_lshl_add_u32 v29, v29, 3, v60
	s_waitcnt lgkmcnt(1)
	v_add_u32_e32 v12, 0xff, v12
	v_add_u32_e32 v3, v3, v22
	v_lshrrev_b32_e32 v27, 8, v10
	v_cndmask_b32_e64 v10, 0, v28, s[4:5]
	v_cmp_lt_u32_e64 s[4:5], s6, v11
	v_bfe_u32 v60, v12, 5, 3
	v_lshrrev_b32_e32 v30, 8, v12
	v_add_u32_e32 v60, -3, v60
	v_max_i32_e32 v60, 0, v60
	v_lshl_add_u32 v30, v30, 3, v60
	v_add_u32_e32 v13, 0xff, v13
	v_add_u32_e32 v5, v5, v3
	v_lshrrev_b32_e32 v28, 8, v11
	v_cndmask_b32_e64 v11, 0, v29, s[4:5]
	v_cmp_lt_u32_e64 s[4:5], s6, v12
	v_bfe_u32 v60, v13, 5, 3
	v_lshrrev_b32_e32 v31, 8, v13
	v_add_u32_e32 v60, -3, v60
	v_max_i32_e32 v60, 0, v60
	v_lshl_add_u32 v31, v31, 3, v60
	v_add_u32_e32 v14, 0xff, v14
	v_add_u32_e32 v25, v25, v5
	v_lshrrev_b32_e32 v29, 8, v12
	v_cndmask_b32_e64 v12, 0, v30, s[4:5]
	v_cmp_lt_u32_e64 s[4:5], s6, v13
	v_bfe_u32 v60, v14, 5, 3
	v_lshrrev_b32_e32 v32, 8, v14
	v_add_u32_e32 v60, -3, v60
	v_max_i32_e32 v60, 0, v60
	v_lshl_add_u32 v32, v32, 3, v60
	v_add_u32_e32 v15, 0xff, v15
	v_add_u32_e32 v26, v26, v25
	v_lshrrev_b32_e32 v30, 8, v13
	v_cndmask_b32_e64 v13, 0, v31, s[4:5]
	v_cmp_lt_u32_e64 s[4:5], s6, v14
	v_bfe_u32 v60, v15, 5, 3
	v_lshrrev_b32_e32 v33, 8, v15
	v_add_u32_e32 v60, -3, v60
	v_max_i32_e32 v60, 0, v60
	v_lshl_add_u32 v33, v33, 3, v60
	s_waitcnt lgkmcnt(0)
	v_add_u32_e32 v16, 0xff, v16
	v_add_u32_e32 v27, v27, v26
	v_lshrrev_b32_e32 v31, 8, v14
	v_cndmask_b32_e64 v14, 0, v32, s[4:5]
	v_cmp_lt_u32_e64 s[4:5], s6, v15
	v_bfe_u32 v60, v16, 5, 3
	v_lshrrev_b32_e32 v34, 8, v16
	v_add_u32_e32 v60, -3, v60
	v_max_i32_e32 v60, 0, v60
	v_lshl_add_u32 v34, v34, 3, v60
	v_add_u32_e32 v17, 0xff, v17
	v_add_u32_e32 v28, v28, v27
	v_lshrrev_b32_e32 v32, 8, v15
	v_cndmask_b32_e64 v15, 0, v33, s[4:5]
	v_cmp_lt_u32_e64 s[4:5], s6, v16
	v_bfe_u32 v60, v17, 5, 3
	v_lshrrev_b32_e32 v35, 8, v17
	v_add_u32_e32 v60, -3, v60
	v_max_i32_e32 v60, 0, v60
	v_lshl_add_u32 v35, v35, 3, v60
	v_add_u32_e32 v18, 0xff, v18
	v_add_u32_e32 v29, v29, v28
	v_lshrrev_b32_e32 v33, 8, v16
	v_cndmask_b32_e64 v16, 0, v34, s[4:5]
	v_cmp_lt_u32_e64 s[4:5], s6, v17
	v_bfe_u32 v60, v18, 5, 3
	v_lshrrev_b32_e32 v36, 8, v18
	v_add_u32_e32 v60, -3, v60
	v_max_i32_e32 v60, 0, v60
	v_lshl_add_u32 v36, v36, 3, v60
	v_add_u32_e32 v19, 0xff, v19
	v_add_u32_e32 v30, v30, v29
	v_lshrrev_b32_e32 v34, 8, v17
	v_cndmask_b32_e64 v17, 0, v35, s[4:5]
	v_cmp_lt_u32_e64 s[4:5], s6, v18
	v_bfe_u32 v60, v19, 5, 3
	v_lshrrev_b32_e32 v37, 8, v19
	v_add_u32_e32 v60, -3, v60
	v_max_i32_e32 v60, 0, v60
	v_lshl_add_u32 v37, v37, 3, v60
	v_add_u32_e32 v31, v31, v30
	v_lshrrev_b32_e32 v35, 8, v18
	v_cndmask_b32_e64 v18, 0, v36, s[4:5]
	v_cmp_lt_u32_e64 s[4:5], s6, v19
	v_add_u32_e32 v32, v32, v31
	v_lshrrev_b32_e32 v36, 8, v19
	v_cndmask_b32_e64 v19, 0, v37, s[4:5]
	v_add_u32_e32 v37, -1, v6
	v_add_u32_e32 v33, v33, v32
	v_cmp_lt_i32_e64 s[4:5], v37, v7
	v_add_u32_e32 v47, v2, v23
	v_add_u32_e32 v34, v34, v33
	v_cndmask_b32_e64 v37, v37, v6, s[4:5]
	s_add_i32 s17, 0, 0x22800
	v_add_u32_e32 v4, v4, v47
	v_or_b32_e32 v2, 20, v20
	v_add_u32_e32 v35, v35, v34
	v_lshlrev_b32_e32 v37, 2, v37
	v_cmp_lt_i32_e64 s[4:5], v38, v7
	v_add_u32_e32 v39, -4, v6
	v_add_u32_e32 v48, s16, v2
	v_add_u32_e32 v49, s17, v2
	v_add_u32_e32 v50, v8, v4
	v_or_b32_e32 v2, 28, v20
	v_add_u32_e32 v8, v36, v35
	v_cndmask_b32_e64 v38, v38, v6, s[4:5]
	v_cmp_lt_i32_e64 s[4:5], v39, v7
	v_add_u32_e32 v40, -8, v6
	v_add_u32_e32 v52, s16, v2
	v_add_u32_e32 v53, s17, v2
	ds_bpermute_b32 v2, v37, v8
	v_cndmask_b32_e64 v39, v39, v6, s[4:5]
	v_cmp_lt_i32_e64 s[4:5], v40, v7
	v_add_u32_e32 v41, -16, v6
	v_subrev_u32_e32 v42, 32, v6
	v_cndmask_b32_e64 v40, v40, v6, s[4:5]
	v_cmp_lt_i32_e64 s[4:5], v41, v7
	v_lshlrev_b32_e32 v38, 2, v38
	v_add_u32_e32 v51, v9, v50
	v_cndmask_b32_e64 v41, v41, v6, s[4:5]
	v_cmp_lt_i32_e64 s[4:5], v42, v7
	v_add_u32_e32 v36, v10, v51
	v_or_b32_e32 v9, 36, v20
	v_cndmask_b32_e64 v42, v42, v6, s[4:5]
	v_cmp_eq_u32_e64 s[4:5], 0, v1
	v_cmp_gt_u32_e64 s[6:7], 2, v1
	v_add_u32_e32 v54, v11, v36
	s_waitcnt lgkmcnt(0)
	v_cndmask_b32_e64 v2, v2, 0, s[4:5]
	v_add_u32_e32 v2, v8, v2
	ds_bpermute_b32 v10, v38, v2
	v_add_u32_e32 v11, s16, v9
	v_add_u32_e32 v55, s17, v9
	v_lshlrev_b32_e32 v39, 2, v39
	v_cmp_gt_u32_e64 s[8:9], 4, v1
	s_waitcnt lgkmcnt(0)
	v_cndmask_b32_e64 v9, v10, 0, s[6:7]
	v_add_u32_e32 v2, v2, v9
	ds_bpermute_b32 v9, v39, v2
	v_lshlrev_b32_e32 v40, 2, v40
	v_cmp_gt_u32_e64 s[10:11], 8, v1
	v_lshlrev_b32_e32 v41, 2, v41
	v_add_u32_e32 v56, v12, v54
	s_waitcnt lgkmcnt(0)
	v_cndmask_b32_e64 v9, v9, 0, s[8:9]
	v_add_u32_e32 v2, v9, v2
	ds_bpermute_b32 v9, v40, v2
	v_add_u32_e32 v13, v13, v56
	v_add_u32_e32 v14, v14, v13
	v_add_u32_e32 v15, v15, v14
	v_cmp_gt_u32_e64 s[12:13], 16, v1
	s_waitcnt lgkmcnt(0)
	v_cndmask_b32_e64 v9, v9, 0, s[10:11]
	v_add_u32_e32 v2, v9, v2
	ds_bpermute_b32 v9, v41, v2
	v_add_u32_e32 v16, v16, v15
	v_lshlrev_b32_e32 v42, 2, v42
	v_add_u32_e32 v17, v17, v16
	v_add_u32_e32 v18, v18, v17
	s_waitcnt lgkmcnt(0)
	v_cndmask_b32_e64 v9, v9, 0, s[12:13]
	v_add_u32_e32 v2, v9, v2
	ds_bpermute_b32 v9, v42, v2
	v_add_u32_e32 v19, v19, v18
	ds_bpermute_b32 v37, v37, v19
	v_or_b32_e32 v10, 44, v20
	v_add_u32_e32 v12, s16, v10
	s_waitcnt lgkmcnt(1)
	v_cndmask_b32_e64 v9, v9, 0, vcc
	v_add_u32_e32 v2, v9, v2
	v_add_u32_e32 v57, s17, v10
	v_or_b32_e32 v10, 52, v20
	v_sub_u32_e32 v8, v2, v8
	s_waitcnt lgkmcnt(0)
	v_cndmask_b32_e64 v9, v37, 0, s[4:5]
	v_add_u32_e32 v58, s16, v10
	v_add_u32_e32 v59, s17, v10
	v_add_u32_e32 v10, v8, v22
	v_add_u32_e32 v22, v19, v9
	ds_bpermute_b32 v37, v38, v22
	v_add_u32_e32 v43, s16, v20
	v_add_u32_e32 v9, v8, v21
	ds_write_b96 v43, v[8:10]
	v_or_b32_e32 v45, 12, v20
	s_waitcnt lgkmcnt(1)
	v_cndmask_b32_e64 v9, v37, 0, s[6:7]
	v_add_u32_e32 v9, v22, v9
	ds_bpermute_b32 v10, v39, v9
	v_add_u32_e32 v46, s16, v45
	v_add_u32_e32 v5, v8, v5
	v_add_u32_e32 v3, v8, v3
	ds_write2_b32 v46, v3, v5 offset1:1
	v_add_u32_e32 v3, v8, v26
	v_add_u32_e32 v5, v8, v25
	ds_write2_b32 v48, v5, v3 offset1:1
	s_waitcnt lgkmcnt(2)
	v_cndmask_b32_e64 v3, v10, 0, s[8:9]
	v_add_u32_e32 v3, v9, v3
	ds_bpermute_b32 v5, v40, v3
	v_add_u32_e32 v9, v8, v28
	v_add_u32_e32 v10, v8, v27
	ds_write2_b32 v52, v10, v9 offset1:1
	v_add_u32_e32 v9, v8, v30
	s_waitcnt lgkmcnt(1)
	v_cndmask_b32_e64 v5, v5, 0, s[10:11]
	v_add_u32_e32 v3, v3, v5
	ds_bpermute_b32 v5, v41, v3
	v_add_u32_e32 v10, v8, v29
	ds_write2_b32 v11, v10, v9 offset1:1
	v_add_u32_e32 v9, v8, v32
	v_add_u32_e32 v10, v8, v31
	s_waitcnt lgkmcnt(1)
	v_cndmask_b32_e64 v5, v5, 0, s[12:13]
	v_add_u32_e32 v3, v5, v3
	ds_bpermute_b32 v5, v42, v3
	ds_write2_b32 v12, v10, v9 offset1:1
	v_add_u32_e32 v9, v8, v34
	v_add_u32_e32 v10, v8, v33
	ds_write2_b32 v58, v10, v9 offset1:1
	s_waitcnt lgkmcnt(2)
	v_cndmask_b32_e64 v5, v5, 0, vcc
	v_add_u32_e32 v3, v5, v3
	v_sub_u32_e32 v10, v3, v19
	v_add_u32_e32 v45, s17, v45
	v_add_u32_e32 v4, v10, v4
	v_add_u32_e32 v5, v10, v47
	ds_write2_b32 v45, v5, v4 offset1:1
	v_add_u32_e32 v4, v10, v51
	v_add_u32_e32 v5, v10, v50
	ds_write2_b32 v49, v5, v4 offset1:1
	v_add_u32_e32 v4, v10, v54
	v_add_u32_e32 v5, v10, v36
	ds_write2_b32 v53, v5, v4 offset1:1
	v_add_u32_e32 v4, v10, v13
	v_add_u32_e32 v5, v10, v56
	ds_write2_b32 v55, v5, v4 offset1:1
	v_add_u32_e32 v4, v10, v15
	v_add_u32_e32 v5, v10, v14
	ds_write2_b32 v57, v5, v4 offset1:1
	v_add_u32_e32 v4, v10, v17
	v_add_u32_e32 v5, v10, v16
	ds_write2_b32 v59, v5, v4 offset1:1
	v_or_b32_e32 v5, 60, v20
	v_add_u32_e32 v4, v8, v35
	v_add_u32_e32 v8, s16, v5
	v_add_u32_e32 v44, s17, v20
	v_add_u32_e32 v12, v10, v23
	v_add_u32_e32 v11, v10, v24
	ds_write_b32 v8, v4
	v_add_u32_e32 v4, v10, v18
	v_add_u32_e32 v5, s17, v5
	v_cmp_eq_u32_e32 vcc, 63, v1
	ds_write_b96 v44, v[10:12]
	ds_write_b32 v5, v4
	s_and_saveexec_b64 s[4:5], vcc
	s_cbranch_execz .LBB0_792
	s_add_i32 s6, 0, 0x22400
	v_mov_b32_e32 v4, s6
	s_add_i32 s6, 0, 0x23800
	ds_write_b32 v4, v2
	v_mov_b32_e32 v2, s6
	ds_write_b32 v2, v3

.LBB0_798:
	s_add_i32 s7, s5, s4
	s_ashr_i32 s7, s7, 1
	s_lshl_b32 s10, s7, 2
	s_add_i32 s10, s10, 0
	s_add_i32 s10, s10, 0x22800
	v_mov_b32_e32 v4, s10
	ds_read_b32 v4, v4
	s_waitcnt lgkmcnt(0)
	v_readfirstlane_b32 s10, v4
	s_cmp_gt_u32 s10, s6
	s_cselect_b32 s5, s7, s5
	s_cselect_b32 s4, s4, s7
	s_sub_i32 s7, s5, s4
	s_cmp_gt_i32 s7, 1
	s_cbranch_scc1 .LBB0_798
	s_lshl_b32 s4, s4, 2
	s_add_i32 s4, s4, 0
	s_add_i32 s5, s4, 0x21400
	s_add_i32 s4, s4, 0x22800
	v_mov_b32_e32 v4, s5
	v_mov_b32_e32 v8, s4
	ds_read2_b32 v[4:5], v4 offset1:1
	ds_read_b32 v8, v8
	s_waitcnt lgkmcnt(1)
	v_readfirstlane_b32 s4, v4
	s_waitcnt lgkmcnt(0)
	v_readfirstlane_b32 s10, v8
	v_readfirstlane_b32 s5, v5
	s_add_i32 s11, s10, 4
	s_sub_i32 s10, s6, s10
	s_sub_i32 s7, s5, s4
	s_add_i32 s10, s10, 3
	s_lshr_b32 s10, s10, 3
	s_cmp_lt_u32 s11, s6
	s_cselect_b32 s6, s10, 0
	s_add_i32 s4, s6, s4
	s_cmp_lt_u32 s6, s7
	s_cselect_b32 s66, s4, s5

.LBB0_805:
	s_add_i32 s7, s5, s4
	s_ashr_i32 s7, s7, 1
	s_lshl_b32 s8, s7, 2
	s_add_i32 s8, s8, 0
	s_add_i32 s8, s8, 0x22800
	v_mov_b32_e32 v2, s8
	ds_read_b32 v2, v2
	s_waitcnt lgkmcnt(0)
	v_readfirstlane_b32 s8, v2
	s_cmp_gt_u32 s8, s6
	s_cselect_b32 s5, s7, s5
	s_cselect_b32 s4, s4, s7
	s_sub_i32 s7, s5, s4
	s_cmp_gt_i32 s7, 1
	s_cbranch_scc1 .LBB0_805
	s_lshl_b32 s4, s4, 2
	s_add_i32 s4, s4, 0
	s_add_i32 s5, s4, 0x21400
	s_add_i32 s4, s4, 0x22800
	v_mov_b32_e32 v2, s5
	v_mov_b32_e32 v4, s4
	ds_read2_b32 v[2:3], v2 offset1:1
	ds_read_b32 v4, v4
	s_waitcnt lgkmcnt(1)
	v_sub_u32_e32 v5, v3, v2
	s_waitcnt lgkmcnt(0)
	v_add_u32_e32 v8, 4, v4
	v_sub_u32_e32 v4, s6, v4
	v_add_u32_e32 v4, 3, v4
	v_lshrrev_b32_e32 v4, 3, v4
	v_cmp_gt_u32_e32 vcc, s6, v8
	s_nop 1
	v_cndmask_b32_e32 v4, 0, v4, vcc
	v_add_u32_e32 v2, v4, v2
	v_cmp_lt_u32_e32 vcc, v4, v5
	s_nop 1
	v_cndmask_b32_e32 v186, v3, v2, vcc
